# step B: the four V-fragment reads issue before the eight P packs (packs run in the LDS shadow)
# baseline (speedup 1.0000x reference)
.LBB0_464:
	s_add_i32 s4, s62, 1
	s_cmp_lg_u32 s62, 2
	s_cselect_b32 s4, s4, 0
	s_add_i32 s5, s10, 1
	s_cmp_lg_u32 s10, 2
	s_cselect_b32 s5, s5, 0
	s_lshl_b32 s62, s5, 14
	v_add_u32_e32 v198, s62, v219
	v_add_u32_e32 v227, v198, v149
	ds_read_b128 v[236:239], v227 offset:49152
	ds_read_b128 v[240:243], v227 offset:53248
	ds_read_b128 v[86:89], v227 offset:57344
	ds_read_b128 v[228:231], v227 offset:61440
	v_cvt_pk_bf16_f32 v66, v66, v67
	v_cvt_pk_bf16_f32 v67, v68, v69
	v_cvt_pk_bf16_f32 v68, v70, v71
	v_cvt_pk_bf16_f32 v69, v82, v83
	v_cvt_pk_bf16_f32 v74, v74, v75
	v_cvt_pk_bf16_f32 v75, v76, v77
	v_cvt_pk_bf16_f32 v76, v78, v79
	v_cvt_pk_bf16_f32 v77, v80, v81
	s_lshl_b32 s10, s4, 14
	s_cmp_gt_i32 s34, s48
	s_waitcnt lgkmcnt(2)
	v_mfma_f32_32x32x16_bf16 v[50:65], v[236:239], v[66:69], v[50:65]
	v_add_u32_e32 v70, v198, v208
	ds_read_b128 v[78:81], v70 offset:49152
	v_mfma_f32_32x32x16_bf16 v[34:49], v[240:243], v[66:69], v[34:49]
	ds_read_b128 v[232:235], v70 offset:53248
	s_waitcnt lgkmcnt(2)
	v_mfma_f32_32x32x16_bf16 v[18:33], v[86:89], v[66:69], v[18:33]
	ds_read_b128 v[86:89], v70 offset:57344
	v_mfma_f32_32x32x16_bf16 v[2:17], v[228:231], v[66:69], v[2:17]
	ds_read_b128 v[82:85], v70 offset:61440
	s_waitcnt lgkmcnt(2)
	v_mfma_f32_32x32x16_bf16 v[50:65], v[78:81], v[74:77], v[50:65]
	v_add_u32_e32 v227, v198, v209
	ds_read_b128 v[78:81], v227 offset:49152
	v_mfma_f32_32x32x16_bf16 v[34:49], v[232:235], v[74:77], v[34:49]
	s_cbranch_scc1 .LBB0_466
	s_cmp_lt_i32 s61, s39
	s_movk_i32 s79, 0xc0
	s_cselect_b32 s79, s79, 0x140
	s_add_i32 s80, s60, s79
	s_ashr_i32 s81, s80, 31
	s_lshl_b64 s[80:81], s[80:81], 12
	s_add_i32 s60, s10, 0xffffc000
	s_cmp_lg_u32 s4, 0
	s_cselect_b32 s60, s60, 0x8000
	v_lshl_add_u64 v[66:67], v[202:203], 0, s[80:81]
	s_add_i32 s60, s7, s60
	s_mov_b32 m0, s60
	v_lshl_add_u64 v[68:69], v[66:67], 0, s[30:31]
	global_load_lds_dwordx4 v[68:69], off
	s_add_i32 m0, s60, 0x2000
	v_lshl_add_u64 v[66:67], v[66:67], 0, s[36:37]
	global_load_lds_dwordx4 v[66:67], off
